# P4 hand-off: no invalidate on the same-XCD path (no stale L1 line can exist there)
# baseline (speedup 1.0000x reference)
.Lph_nofence:
	s_mov_b64 exec, -1
